# phase-0 weight conversion: read-once f32 loads and bf16 stores issued nt (on top of nt residual-stream stores)
# baseline (speedup 1.0000x reference)
; DEVI void convT(const float* src, int K, int N, u16* dst, int Npad, int mode, const float* gk, float* tile, int first) {
;     ...
;         for (int i = tid; i < 1024; i += 512) { const int kk = i >> 4, n4 = (i & 15) * 4, n = n0 + n4;
;             f32x4 v = (f32x4){0.f, 0.f, 0.f, 0.f}; if (n < N) { v = *(const f32x4*)(src + (size_t)(k0 + kk) * N + n); if (gk) v = v * gk[k0 + kk]; }
;             float* tp = tile + kk * 65 + n4; tp[0] = v[0]; tp[1] = v[1]; tp[2] = v[2]; tp[3] = v[3]; }
.Lcv_ret0:
	v_cmp_gt_i32_e32 vcc, s63, v3
	v_add_u32_e32 v70, s64, v2
	s_nop 1
	v_cndmask_b32_e32 v70, 0, v70, vcc
	v_mad_u32_u24 v70, v1, s62, v70
	global_load_dwordx4 v[20:23], v70, s[60:61] nt
	s_lshl_b32 s2, s62, 5
	s_add_u32 s60, s60, s2
	s_addc_u32 s61, s61, 0
	global_load_dwordx4 v[24:27], v70, s[60:61] nt
	global_load_dword v28, v4, s[66:67]
	global_load_dword v29, v4, s[66:67] offset:128
	s_mov_b64 s[40:41], s[70:71]
	s_mov_b32 s42, s63
	s_mov_b32 s43, s68
	s_mul_i32 s38, 1, 248
	s_add_u32 s38, s38, s39
	s_mov_b32 s79, 1
	s_branch .Lcv_desc
.Lcv_ret1:
	v_cmp_gt_i32_e32 vcc, s63, v3
	v_add_u32_e32 v70, s64, v2
	s_nop 1
	v_cndmask_b32_e32 v70, 0, v70, vcc
	v_mad_u32_u24 v70, v1, s62, v70
	global_load_dwordx4 v[32:35], v70, s[60:61] nt
	s_lshl_b32 s2, s62, 5
	s_add_u32 s60, s60, s2
	s_addc_u32 s61, s61, 0
	global_load_dwordx4 v[36:39], v70, s[60:61] nt
	global_load_dword v40, v4, s[66:67]
	global_load_dword v41, v4, s[66:67] offset:128
	s_mov_b64 s[44:45], s[70:71]
	s_mov_b32 s50, s63
	s_mov_b32 s51, s68
	s_mul_i32 s38, 2, 248
	s_add_u32 s38, s38, s39
	s_mov_b32 s79, 2
	s_branch .Lcv_desc
.Lcv_ret2:
	v_cmp_gt_i32_e32 vcc, s63, v3
	v_add_u32_e32 v70, s64, v2
	s_nop 1
	v_cndmask_b32_e32 v70, 0, v70, vcc
	v_mad_u32_u24 v70, v1, s62, v70
	global_load_dwordx4 v[44:47], v70, s[60:61] nt
	s_lshl_b32 s2, s62, 5
	s_add_u32 s60, s60, s2
	s_addc_u32 s61, s61, 0
	global_load_dwordx4 v[48:51], v70, s[60:61] nt
	global_load_dword v52, v4, s[66:67]
	global_load_dword v53, v4, s[66:67] offset:128
	s_mov_b64 s[52:53], s[70:71]
	s_mov_b32 s54, s63
	s_mov_b32 s55, s68
	s_mov_b32 s36, 0

; DEVI void convT(const float* src, int K, int N, u16* dst, int Npad, int mode, const float* gk, float* tile, int first) {
;     ...
;         for (int i = tid; i < 1024; i += 512) { const int kk = i >> 4, n4 = (i & 15) * 4, n = n0 + n4;
;             f32x4 v = (f32x4){0.f, 0.f, 0.f, 0.f}; if (n < N) { v = *(const f32x4*)(src + (size_t)(k0 + kk) * N + n); if (gk) v = v * gk[k0 + kk]; }
;             float* tp = tile + kk * 65 + n4; tp[0] = v[0]; tp[1] = v[1]; tp[2] = v[2]; tp[3] = v[3]; }
.Lcv_ret3:
	v_cmp_gt_i32_e32 vcc, s63, v3
	v_add_u32_e32 v70, s64, v2
	s_nop 1
	v_cndmask_b32_e32 v70, 0, v70, vcc
	v_mad_u32_u24 v70, v1, s62, v70
	global_load_dwordx4 v[56:59], v70, s[60:61] nt
	s_lshl_b32 s2, s62, 5
	s_add_u32 s60, s60, s2
	s_addc_u32 s61, s61, 0
	global_load_dwordx4 v[60:63], v70, s[60:61] nt
	global_load_dword v64, v4, s[66:67]
	global_load_dword v65, v4, s[66:67] offset:128
	s_mov_b64 s[56:57], s[70:71]
	s_mov_b32 s58, s63
	s_mov_b32 s59, s68
	s_waitcnt vmcnt(12)
	s_bitcmp1_b32 s43, 2
	s_cbranch_scc0 .Lcv_nogk0
	v_mul_f32_e32 v20, v20, v28
	v_mul_f32_e32 v21, v21, v28
	v_mul_f32_e32 v22, v22, v28
	v_mul_f32_e32 v23, v23, v28
	v_mul_f32_e32 v24, v24, v29
	v_mul_f32_e32 v25, v25, v29
	v_mul_f32_e32 v26, v26, v29
	v_mul_f32_e32 v27, v27, v29

; DEVI unsigned cvt_pk(float lo, float hi) { f32v2_t f = {lo, hi}; bf16v2_t v = __builtin_convertvector(f, bf16v2_t); return __builtin_bit_cast(unsigned, v); }
; DEVI void convT(const float* src, int K, int N, u16* dst, int Npad, int mode, const float* gk, float* tile, int first) {
;     ...
;         if (mode == 3) { const int kk = tid >> 3, n8 = (tid & 7) * 8; const float* tp = tile + kk * 65 + n8;
;           u32x4 w; w.x = cvt_pk(tp[0], tp[1]); w.y = cvt_pk(tp[2], tp[3]); w.z = cvt_pk(tp[4], tp[5]); w.w = cvt_pk(tp[6], tp[7]);
;           *(u32x4*)(dst + (size_t)(k0 + kk) * N + n0 + n8) = w; }
;         else { const int nn = tid >> 3, k8 = (tid & 7) * 8; const int n = n0 + nn;
;           int row = n; if (mode == 1) row = 256 * (n >> 7) + (n & 127); else if (mode == 2) row = 256 * (n >> 7) + 128 + (n & 127);
;           u32x4 w; w.x = cvt_pk(tile[(k8 + 0) * 65 + nn], tile[(k8 + 1) * 65 + nn]); w.y = cvt_pk(tile[(k8 + 2) * 65 + nn], tile[(k8 + 3) * 65 + nn]);
;           w.z = cvt_pk(tile[(k8 + 4) * 65 + nn], tile[(k8 + 5) * 65 + nn]); w.w = cvt_pk(tile[(k8 + 6) * 65 + nn], tile[(k8 + 7) * 65 + nn]);
;           *(u32x4*)(dst + (size_t)row * K + k0 + k8) = w; }
.Lcv_k0:
	v_mad_u32_u24 v71, v16, s2, v17
	s_waitcnt lgkmcnt(0)
	v_cvt_pk_bf16_f32 v72, v72, v73
	v_cvt_pk_bf16_f32 v73, v74, v75
	v_cvt_pk_bf16_f32 v74, v76, v77
	v_cvt_pk_bf16_f32 v75, v78, v79
	global_store_dwordx4 v71, v[72:75], s[40:41] nt
	s_branch .Lcv_st0
.Lcv_m30:
	ds_read2_b32 v[72:73], v14 offset1:1
	ds_read2_b32 v[74:75], v14 offset0:2 offset1:3
	ds_read2_b32 v[76:77], v14 offset0:4 offset1:5
	ds_read2_b32 v[78:79], v14 offset0:6 offset1:7
	s_waitcnt lgkmcnt(0)
	v_cvt_pk_bf16_f32 v72, v72, v73
	v_cvt_pk_bf16_f32 v73, v74, v75
	v_cvt_pk_bf16_f32 v74, v76, v77
	v_cvt_pk_bf16_f32 v75, v78, v79
	global_store_dwordx4 v18, v[72:75], s[40:41] nt

; DEVI void convT(const float* src, int K, int N, u16* dst, int Npad, int mode, const float* gk, float* tile, int first) {
;     ...
;         for (int i = tid; i < 1024; i += 512) { const int kk = i >> 4, n4 = (i & 15) * 4, n = n0 + n4;
;             f32x4 v = (f32x4){0.f, 0.f, 0.f, 0.f}; if (n < N) { v = *(const f32x4*)(src + (size_t)(k0 + kk) * N + n); if (gk) v = v * gk[k0 + kk]; }
;             float* tp = tile + kk * 65 + n4; tp[0] = v[0]; tp[1] = v[1]; tp[2] = v[2]; tp[3] = v[3]; }
.Lcv_ret4:
	v_cmp_gt_i32_e32 vcc, s63, v3
	v_add_u32_e32 v70, s64, v2
	s_nop 1
	v_cndmask_b32_e32 v70, 0, v70, vcc
	v_mad_u32_u24 v70, v1, s62, v70
	global_load_dwordx4 v[20:23], v70, s[60:61] nt
	s_lshl_b32 s2, s62, 5
	s_add_u32 s60, s60, s2
	s_addc_u32 s61, s61, 0
	global_load_dwordx4 v[24:27], v70, s[60:61] nt
	global_load_dword v28, v4, s[66:67]
	global_load_dword v29, v4, s[66:67] offset:128
	s_mov_b64 s[40:41], s[70:71]
	s_mov_b32 s42, s63
	s_mov_b32 s43, s68
	s_waitcnt vmcnt(12)
	s_bitcmp1_b32 s51, 2
	s_cbranch_scc0 .Lcv_nogk1
	v_mul_f32_e32 v32, v32, v40
	v_mul_f32_e32 v33, v33, v40
	v_mul_f32_e32 v34, v34, v40
	v_mul_f32_e32 v35, v35, v40
	v_mul_f32_e32 v36, v36, v41
	v_mul_f32_e32 v37, v37, v41
	v_mul_f32_e32 v38, v38, v41
	v_mul_f32_e32 v39, v39, v41

; DEVI unsigned cvt_pk(float lo, float hi) { f32v2_t f = {lo, hi}; bf16v2_t v = __builtin_convertvector(f, bf16v2_t); return __builtin_bit_cast(unsigned, v); }
; DEVI void convT(const float* src, int K, int N, u16* dst, int Npad, int mode, const float* gk, float* tile, int first) {
;     ...
;         if (mode == 3) { const int kk = tid >> 3, n8 = (tid & 7) * 8; const float* tp = tile + kk * 65 + n8;
;           u32x4 w; w.x = cvt_pk(tp[0], tp[1]); w.y = cvt_pk(tp[2], tp[3]); w.z = cvt_pk(tp[4], tp[5]); w.w = cvt_pk(tp[6], tp[7]);
;           *(u32x4*)(dst + (size_t)(k0 + kk) * N + n0 + n8) = w; }
;         else { const int nn = tid >> 3, k8 = (tid & 7) * 8; const int n = n0 + nn;
;           int row = n; if (mode == 1) row = 256 * (n >> 7) + (n & 127); else if (mode == 2) row = 256 * (n >> 7) + 128 + (n & 127);
;           u32x4 w; w.x = cvt_pk(tile[(k8 + 0) * 65 + nn], tile[(k8 + 1) * 65 + nn]); w.y = cvt_pk(tile[(k8 + 2) * 65 + nn], tile[(k8 + 3) * 65 + nn]);
;           w.z = cvt_pk(tile[(k8 + 4) * 65 + nn], tile[(k8 + 5) * 65 + nn]); w.w = cvt_pk(tile[(k8 + 6) * 65 + nn], tile[(k8 + 7) * 65 + nn]);
;           *(u32x4*)(dst + (size_t)row * K + k0 + k8) = w; }
.Lcv_k1:
	v_mad_u32_u24 v71, v16, s2, v17
	s_waitcnt lgkmcnt(0)
	v_cvt_pk_bf16_f32 v72, v72, v73
	v_cvt_pk_bf16_f32 v73, v74, v75
	v_cvt_pk_bf16_f32 v74, v76, v77
	v_cvt_pk_bf16_f32 v75, v78, v79
	global_store_dwordx4 v71, v[72:75], s[44:45] nt
	s_branch .Lcv_st1
.Lcv_m31:
	ds_read2_b32 v[72:73], v15 offset1:1
	ds_read2_b32 v[74:75], v15 offset0:2 offset1:3
	ds_read2_b32 v[76:77], v15 offset0:4 offset1:5
	ds_read2_b32 v[78:79], v15 offset0:6 offset1:7
	s_waitcnt lgkmcnt(0)
	v_cvt_pk_bf16_f32 v72, v72, v73
	v_cvt_pk_bf16_f32 v73, v74, v75
	v_cvt_pk_bf16_f32 v74, v76, v77
	v_cvt_pk_bf16_f32 v75, v78, v79
	global_store_dwordx4 v18, v[72:75], s[44:45] nt

; DEVI void convT(const float* src, int K, int N, u16* dst, int Npad, int mode, const float* gk, float* tile, int first) {
;     ...
;         for (int i = tid; i < 1024; i += 512) { const int kk = i >> 4, n4 = (i & 15) * 4, n = n0 + n4;
;             f32x4 v = (f32x4){0.f, 0.f, 0.f, 0.f}; if (n < N) { v = *(const f32x4*)(src + (size_t)(k0 + kk) * N + n); if (gk) v = v * gk[k0 + kk]; }
;             float* tp = tile + kk * 65 + n4; tp[0] = v[0]; tp[1] = v[1]; tp[2] = v[2]; tp[3] = v[3]; }
.Lcv_ret5:
	v_cmp_gt_i32_e32 vcc, s63, v3
	v_add_u32_e32 v70, s64, v2
	s_nop 1
	v_cndmask_b32_e32 v70, 0, v70, vcc
	v_mad_u32_u24 v70, v1, s62, v70
	global_load_dwordx4 v[32:35], v70, s[60:61] nt
	s_lshl_b32 s2, s62, 5
	s_add_u32 s60, s60, s2
	s_addc_u32 s61, s61, 0
	global_load_dwordx4 v[36:39], v70, s[60:61] nt
	global_load_dword v40, v4, s[66:67]
	global_load_dword v41, v4, s[66:67] offset:128
	s_mov_b64 s[44:45], s[70:71]
	s_mov_b32 s50, s63
	s_mov_b32 s51, s68
	s_waitcnt vmcnt(12)
	s_bitcmp1_b32 s55, 2
	s_cbranch_scc0 .Lcv_nogk2
	v_mul_f32_e32 v44, v44, v52
	v_mul_f32_e32 v45, v45, v52
	v_mul_f32_e32 v46, v46, v52
	v_mul_f32_e32 v47, v47, v52
	v_mul_f32_e32 v48, v48, v53
	v_mul_f32_e32 v49, v49, v53
	v_mul_f32_e32 v50, v50, v53
	v_mul_f32_e32 v51, v51, v53

; DEVI unsigned cvt_pk(float lo, float hi) { f32v2_t f = {lo, hi}; bf16v2_t v = __builtin_convertvector(f, bf16v2_t); return __builtin_bit_cast(unsigned, v); }
; DEVI void convT(const float* src, int K, int N, u16* dst, int Npad, int mode, const float* gk, float* tile, int first) {
;     ...
;         if (mode == 3) { const int kk = tid >> 3, n8 = (tid & 7) * 8; const float* tp = tile + kk * 65 + n8;
;           u32x4 w; w.x = cvt_pk(tp[0], tp[1]); w.y = cvt_pk(tp[2], tp[3]); w.z = cvt_pk(tp[4], tp[5]); w.w = cvt_pk(tp[6], tp[7]);
;           *(u32x4*)(dst + (size_t)(k0 + kk) * N + n0 + n8) = w; }
;         else { const int nn = tid >> 3, k8 = (tid & 7) * 8; const int n = n0 + nn;
;           int row = n; if (mode == 1) row = 256 * (n >> 7) + (n & 127); else if (mode == 2) row = 256 * (n >> 7) + 128 + (n & 127);
;           u32x4 w; w.x = cvt_pk(tile[(k8 + 0) * 65 + nn], tile[(k8 + 1) * 65 + nn]); w.y = cvt_pk(tile[(k8 + 2) * 65 + nn], tile[(k8 + 3) * 65 + nn]);
;           w.z = cvt_pk(tile[(k8 + 4) * 65 + nn], tile[(k8 + 5) * 65 + nn]); w.w = cvt_pk(tile[(k8 + 6) * 65 + nn], tile[(k8 + 7) * 65 + nn]);
;           *(u32x4*)(dst + (size_t)row * K + k0 + k8) = w; }
.Lcv_k2:
	v_mad_u32_u24 v71, v16, s2, v17
	s_waitcnt lgkmcnt(0)
	v_cvt_pk_bf16_f32 v72, v72, v73
	v_cvt_pk_bf16_f32 v73, v74, v75
	v_cvt_pk_bf16_f32 v74, v76, v77
	v_cvt_pk_bf16_f32 v75, v78, v79
	global_store_dwordx4 v71, v[72:75], s[52:53] nt
	s_branch .Lcv_st2
.Lcv_m32:
	ds_read2_b32 v[72:73], v14 offset1:1
	ds_read2_b32 v[74:75], v14 offset0:2 offset1:3
	ds_read2_b32 v[76:77], v14 offset0:4 offset1:5
	ds_read2_b32 v[78:79], v14 offset0:6 offset1:7
	s_waitcnt lgkmcnt(0)
	v_cvt_pk_bf16_f32 v72, v72, v73
	v_cvt_pk_bf16_f32 v73, v74, v75
	v_cvt_pk_bf16_f32 v74, v76, v77
	v_cvt_pk_bf16_f32 v75, v78, v79
	global_store_dwordx4 v18, v[72:75], s[52:53] nt

; DEVI void convT(const float* src, int K, int N, u16* dst, int Npad, int mode, const float* gk, float* tile, int first) {
;     ...
;         for (int i = tid; i < 1024; i += 512) { const int kk = i >> 4, n4 = (i & 15) * 4, n = n0 + n4;
;             f32x4 v = (f32x4){0.f, 0.f, 0.f, 0.f}; if (n < N) { v = *(const f32x4*)(src + (size_t)(k0 + kk) * N + n); if (gk) v = v * gk[k0 + kk]; }
;             float* tp = tile + kk * 65 + n4; tp[0] = v[0]; tp[1] = v[1]; tp[2] = v[2]; tp[3] = v[3]; }
.Lcv_ret6:
	v_cmp_gt_i32_e32 vcc, s63, v3
	v_add_u32_e32 v70, s64, v2
	s_nop 1
	v_cndmask_b32_e32 v70, 0, v70, vcc
	v_mad_u32_u24 v70, v1, s62, v70
	global_load_dwordx4 v[44:47], v70, s[60:61] nt
	s_lshl_b32 s2, s62, 5
	s_add_u32 s60, s60, s2
	s_addc_u32 s61, s61, 0
	global_load_dwordx4 v[48:51], v70, s[60:61] nt
	global_load_dword v52, v4, s[66:67]
	global_load_dword v53, v4, s[66:67] offset:128
	s_mov_b64 s[52:53], s[70:71]
	s_mov_b32 s54, s63
	s_mov_b32 s55, s68
	s_waitcnt vmcnt(12)
	s_bitcmp1_b32 s59, 2
	s_cbranch_scc0 .Lcv_nogk3
	v_mul_f32_e32 v56, v56, v64
	v_mul_f32_e32 v57, v57, v64
	v_mul_f32_e32 v58, v58, v64
	v_mul_f32_e32 v59, v59, v64
	v_mul_f32_e32 v60, v60, v65
	v_mul_f32_e32 v61, v61, v65
	v_mul_f32_e32 v62, v62, v65
	v_mul_f32_e32 v63, v63, v65

; DEVI unsigned cvt_pk(float lo, float hi) { f32v2_t f = {lo, hi}; bf16v2_t v = __builtin_convertvector(f, bf16v2_t); return __builtin_bit_cast(unsigned, v); }
; DEVI void convT(const float* src, int K, int N, u16* dst, int Npad, int mode, const float* gk, float* tile, int first) {
;     ...
;         if (mode == 3) { const int kk = tid >> 3, n8 = (tid & 7) * 8; const float* tp = tile + kk * 65 + n8;
;           u32x4 w; w.x = cvt_pk(tp[0], tp[1]); w.y = cvt_pk(tp[2], tp[3]); w.z = cvt_pk(tp[4], tp[5]); w.w = cvt_pk(tp[6], tp[7]);
;           *(u32x4*)(dst + (size_t)(k0 + kk) * N + n0 + n8) = w; }
;         else { const int nn = tid >> 3, k8 = (tid & 7) * 8; const int n = n0 + nn;
;           int row = n; if (mode == 1) row = 256 * (n >> 7) + (n & 127); else if (mode == 2) row = 256 * (n >> 7) + 128 + (n & 127);
;           u32x4 w; w.x = cvt_pk(tile[(k8 + 0) * 65 + nn], tile[(k8 + 1) * 65 + nn]); w.y = cvt_pk(tile[(k8 + 2) * 65 + nn], tile[(k8 + 3) * 65 + nn]);
;           w.z = cvt_pk(tile[(k8 + 4) * 65 + nn], tile[(k8 + 5) * 65 + nn]); w.w = cvt_pk(tile[(k8 + 6) * 65 + nn], tile[(k8 + 7) * 65 + nn]);
;           *(u32x4*)(dst + (size_t)row * K + k0 + k8) = w; }
.Lcv_k3:
	v_mad_u32_u24 v71, v16, s2, v17
	s_waitcnt lgkmcnt(0)
	v_cvt_pk_bf16_f32 v72, v72, v73
	v_cvt_pk_bf16_f32 v73, v74, v75
	v_cvt_pk_bf16_f32 v74, v76, v77
	v_cvt_pk_bf16_f32 v75, v78, v79
	global_store_dwordx4 v71, v[72:75], s[56:57] nt
	s_branch .Lcv_st3
.Lcv_m33:
	ds_read2_b32 v[72:73], v15 offset1:1
	ds_read2_b32 v[74:75], v15 offset0:2 offset1:3
	ds_read2_b32 v[76:77], v15 offset0:4 offset1:5
	ds_read2_b32 v[78:79], v15 offset0:6 offset1:7
	s_waitcnt lgkmcnt(0)
	v_cvt_pk_bf16_f32 v72, v72, v73
	v_cvt_pk_bf16_f32 v73, v74, v75
	v_cvt_pk_bf16_f32 v74, v76, v77
	v_cvt_pk_bf16_f32 v75, v78, v79
	global_store_dwordx4 v18, v[72:75], s[56:57] nt
